# MLA loops both layers: loop-carried K/V tile pointers and toggled LDS offsets replace the per-step scalar address block (row sums unchanged)
# speedup vs baseline: 1.0080x; 1.0080x over previous
.LBB0_892:
	s_add_i32 s1, s4, 1
	s_xor_b32 s36, s99, 0x6000
	s_add_i32 s36, s69, s36
	s_add_i32 m0, s36, 0x8000
	v_lshl_add_u64 v[66:67], v[160:161], 1, s[38:39]
	global_load_lds_dwordx4 v[66:67], off
	s_add_i32 m0, s36, 0xa000
	v_lshl_add_u64 v[66:67], v[162:163], 1, s[38:39]
	global_load_lds_dwordx4 v[66:67], off
	s_add_i32 m0, s36, 0xc000
	v_lshl_add_u64 v[66:67], v[170:171], 1, s[38:39]
	global_load_lds_dwordx4 v[66:67], off
	s_xor_b32 s36, s98, 0x4000
	s_add_i32 s36, s69, s36
	s_mov_b32 m0, s36
	v_lshl_add_u64 v[66:67], v[172:173], 1, s[28:29]
	global_load_lds_dwordx4 v[66:67], off
	s_add_i32 m0, s36, 0x2000
	v_lshl_add_u64 v[66:67], v[174:175], 1, s[28:29]
	global_load_lds_dwordx4 v[66:67], off
	s_add_u32 s38, s38, 0x30000
	s_addc_u32 s39, s39, 0
	s_add_u32 s28, s28, 0x40000
	s_addc_u32 s29, s29, 0
	s_cmp_eq_u32 s1, 3
	s_cbranch_scc1 .Lmla0_sw
	.Lmla0_swr:
	v_add_u32_e32 v70, s99, v179
	v_add_u32_e32 v71, v70, v178
	ds_read_b128 v[66:69], v71 offset:32768
	v_add_u32_e32 v153, v70, v180
	v_add_u32_e32 v155, v70, v181
	v_add_u32_e32 v157, v70, v182
	v_add_u32_e32 v159, v70, v183
	v_add_u32_e32 v193, v70, v184
	v_add_u32_e32 v198, v70, v185
	v_add_u32_e32 v199, v70, v186
	v_add_u32_e32 v200, v70, v187
	s_waitcnt lgkmcnt(0)
	v_mfma_f32_32x32x16_bf16 v[82:97], v[66:69], v[142:145], 0
	ds_read_b128 v[66:69], v153 offset:32768
	v_add_u32_e32 v201, v70, v188
	v_add_u32_e32 v202, v70, v189
	v_add_u32_e32 v203, v70, v190
	s_waitcnt lgkmcnt(0)
	v_mfma_f32_32x32x16_bf16 v[82:97], v[66:69], v[138:141], v[82:97]
	ds_read_b128 v[66:69], v155 offset:32768
	s_waitcnt lgkmcnt(0)
	v_mfma_f32_32x32x16_bf16 v[82:97], v[66:69], v[134:137], v[82:97]
	ds_read_b128 v[66:69], v157 offset:32768
	s_waitcnt lgkmcnt(0)
	v_mfma_f32_32x32x16_bf16 v[82:97], v[66:69], v[130:133], v[82:97]
	ds_read_b128 v[66:69], v159 offset:32768
	s_waitcnt lgkmcnt(0)
	v_mfma_f32_32x32x16_bf16 v[82:97], v[66:69], v[126:129], v[82:97]
	ds_read_b128 v[66:69], v193 offset:32768
	s_waitcnt lgkmcnt(0)
	v_mfma_f32_32x32x16_bf16 v[82:97], v[66:69], v[122:125], v[82:97]
	ds_read_b128 v[66:69], v198 offset:32768
	s_waitcnt lgkmcnt(0)
	v_mfma_f32_32x32x16_bf16 v[82:97], v[66:69], v[118:121], v[82:97]
	ds_read_b128 v[66:69], v199 offset:32768
	s_waitcnt lgkmcnt(0)
	v_mfma_f32_32x32x16_bf16 v[82:97], v[66:69], v[114:117], v[82:97]
	ds_read_b128 v[66:69], v200 offset:32768
	s_waitcnt lgkmcnt(0)
	v_mfma_f32_32x32x16_bf16 v[82:97], v[66:69], v[110:113], v[82:97]
	ds_read_b128 v[66:69], v201 offset:32768
	s_waitcnt lgkmcnt(0)
	v_mfma_f32_32x32x16_bf16 v[82:97], v[66:69], v[106:109], v[82:97]
	ds_read_b128 v[66:69], v202 offset:32768
	s_waitcnt lgkmcnt(0)
	v_mfma_f32_32x32x16_bf16 v[82:97], v[66:69], v[102:105], v[82:97]
	ds_read_b128 v[66:69], v203 offset:32768
	s_waitcnt lgkmcnt(0)
	v_mfma_f32_32x32x16_bf16 v[82:97], v[66:69], v[98:101], v[82:97]
	ds_read_b128 v[66:69], v71 offset:45056
	ds_read_b128 v[194:197], v153 offset:45056
	s_nop 9
	v_exp_f32_e32 v204, v88
	v_exp_f32_e32 v205, v89
	v_exp_f32_e32 v206, v90
	v_exp_f32_e32 v207, v91
	v_exp_f32_e32 v208, v92
	v_exp_f32_e32 v209, v93
	v_exp_f32_e32 v210, v94
	s_waitcnt lgkmcnt(0)
	v_mfma_f32_32x32x16_bf16 v[66:81], v[66:69], v[142:145], 0
	v_exp_f32_e32 v211, v95
	v_exp_f32_e32 v212, v96
	v_exp_f32_e32 v213, v97
	v_add_u32_e32 v153, s98, v176
	v_cvt_pk_bf16_f32 v88, v210, v211
	v_cvt_pk_bf16_f32 v89, v212, v213
	v_mfma_f32_32x32x16_bf16 v[66:81], v[194:197], v[138:141], v[66:81]
	ds_read_b128 v[194:197], v155 offset:45056
	v_exp_f32_e32 v155, v82
	s_waitcnt lgkmcnt(0)
	v_mfma_f32_32x32x16_bf16 v[66:81], v[194:197], v[134:137], v[66:81]
	ds_read_b128 v[194:197], v157 offset:45056
	v_exp_f32_e32 v157, v83
	s_nop 0
	v_cvt_pk_bf16_f32 v82, v155, v157
	s_waitcnt lgkmcnt(0)
	v_mfma_f32_32x32x16_bf16 v[66:81], v[194:197], v[130:133], v[66:81]
	ds_read_b128 v[194:197], v159 offset:45056
	v_exp_f32_e32 v159, v84
	s_waitcnt lgkmcnt(0)
	v_mfma_f32_32x32x16_bf16 v[66:81], v[194:197], v[126:129], v[66:81]
	ds_read_b128 v[194:197], v193 offset:45056
	v_exp_f32_e32 v193, v85
	v_cvt_pk_bf16_f32 v85, v204, v205
	v_cvt_pk_bf16_f32 v83, v159, v193
	s_nop 1
	v_permlane32_swap_b32_e32 v83, v85
	s_waitcnt lgkmcnt(0)
	v_mfma_f32_32x32x16_bf16 v[66:81], v[194:197], v[122:125], v[66:81]
	ds_read_b128 v[194:197], v198 offset:45056
	s_waitcnt lgkmcnt(0)
	v_mfma_f32_32x32x16_bf16 v[66:81], v[194:197], v[118:121], v[66:81]
	ds_read_b128 v[194:197], v199 offset:45056
	s_waitcnt lgkmcnt(0)
	v_mfma_f32_32x32x16_bf16 v[66:81], v[194:197], v[114:117], v[66:81]
	ds_read_b128 v[194:197], v200 offset:45056
	s_waitcnt lgkmcnt(0)
	v_mfma_f32_32x32x16_bf16 v[66:81], v[194:197], v[110:113], v[66:81]
	ds_read_b128 v[194:197], v201 offset:45056
	s_waitcnt lgkmcnt(0)
	v_mfma_f32_32x32x16_bf16 v[66:81], v[194:197], v[106:109], v[66:81]
	ds_read_b128 v[194:197], v202 offset:45056
	v_exp_f32_e32 v202, v86
	v_cvt_pk_bf16_f32 v86, v206, v207
	s_nop 1
	v_permlane32_swap_b32_e32 v86, v88
	s_waitcnt lgkmcnt(0)
	v_mfma_f32_32x32x16_bf16 v[66:81], v[194:197], v[102:105], v[66:81]
	ds_read_b128 v[194:197], v203 offset:45056
	v_exp_f32_e32 v203, v87
	v_cvt_pk_bf16_f32 v87, v208, v209
	s_nop 1
	v_permlane32_swap_b32_e32 v87, v89
	v_cvt_pk_bf16_f32 v84, v202, v203
	s_nop 1
	v_permlane32_swap_b32_e32 v82, v84
	s_waitcnt lgkmcnt(0)
	v_mfma_f32_32x32x16_bf16 v[66:81], v[194:197], v[98:101], v[66:81]
	ds_read_b64_tr_b16 v[90:91], v153 offset:0
	ds_read_b64_tr_b16 v[92:93], v153 offset:0x800
	ds_read_b64_tr_b16 v[94:95], v153 offset:0x1000
	ds_read_b64_tr_b16 v[96:97], v153 offset:0x1800
	ds_read_b64_tr_b16 v[194:195], v153 offset:0x200
	ds_read_b64_tr_b16 v[196:197], v153 offset:0xa00
	ds_read_b64_tr_b16 v[198:199], v153 offset:0x1200
	ds_read_b64_tr_b16 v[200:201], v153 offset:0x1a00
	s_waitcnt lgkmcnt(4)
	s_nop 0
	v_mfma_f32_32x32x16_bf16 v[2:17], v[82:85], v[90:93], v[2:17]
	s_nop 9
	v_exp_f32_e32 v214, v66
	v_exp_f32_e32 v215, v67
	v_exp_f32_e32 v216, v68
	v_exp_f32_e32 v217, v69
	v_mfma_f32_32x32x16_bf16 v[2:17], v[86:89], v[94:97], v[2:17]
	ds_read_b64_tr_b16 v[66:67], v153 offset:0x400
	ds_read_b64_tr_b16 v[68:69], v153 offset:0xc00
	ds_read_b64_tr_b16 v[90:91], v153 offset:0x1400
	ds_read_b64_tr_b16 v[92:93], v153 offset:0x1c00
	s_waitcnt lgkmcnt(4)
	v_mfma_f32_32x32x16_bf16 v[18:33], v[82:85], v[194:197], v[18:33]
	v_exp_f32_e32 v194, v70
	v_exp_f32_e32 v195, v71
	v_exp_f32_e32 v196, v72
	v_exp_f32_e32 v197, v73
	v_mfma_f32_32x32x16_bf16 v[18:33], v[86:89], v[198:201], v[18:33]
	ds_read_b64_tr_b16 v[70:71], v153 offset:0x600
	ds_read_b64_tr_b16 v[72:73], v153 offset:0xe00
	ds_read_b64_tr_b16 v[94:95], v153 offset:0x1600
	ds_read_b64_tr_b16 v[96:97], v153 offset:0x1e00
	s_waitcnt lgkmcnt(4)
	v_mfma_f32_32x32x16_bf16 v[34:49], v[82:85], v[66:69], v[34:49]
	v_exp_f32_e32 v198, v74
	v_exp_f32_e32 v199, v75
	v_exp_f32_e32 v200, v76
	v_exp_f32_e32 v201, v77
	v_mfma_f32_32x32x16_bf16 v[34:49], v[86:89], v[90:93], v[34:49]
	ds_read_b64_tr_b16 v[66:67], v153 offset:0x2000
	ds_read_b64_tr_b16 v[68:69], v153 offset:0x2800
	ds_read_b64_tr_b16 v[74:75], v153 offset:0x3000
	ds_read_b64_tr_b16 v[76:77], v153 offset:0x3800
	s_waitcnt lgkmcnt(4)
	v_mfma_f32_32x32x16_bf16 v[50:65], v[82:85], v[70:73], v[50:65]
	v_exp_f32_e32 v249, v78
	v_exp_f32_e32 v250, v79
	v_cvt_pk_bf16_f32 v72, v194, v195
	v_cvt_pk_bf16_f32 v73, v196, v197
	v_mfma_f32_32x32x16_bf16 v[50:65], v[86:89], v[94:97], v[50:65]
	v_exp_f32_e32 v251, v80
	v_exp_f32_e32 v248, v81
	v_cvt_pk_bf16_f32 v78, v198, v199
	v_cvt_pk_bf16_f32 v79, v200, v201
	v_cvt_pk_bf16_f32 v80, v249, v250
	v_cvt_pk_bf16_f32 v70, v214, v215
	v_cvt_pk_bf16_f32 v71, v216, v217
	v_permlane32_swap_b32_e32 v78, v80
	v_cvt_pk_bf16_f32 v81, v251, v248
	v_permlane32_swap_b32_e32 v70, v72
	v_permlane32_swap_b32_e32 v71, v73
	s_nop 0
	v_permlane32_swap_b32_e32 v79, v81
	ds_read_b64_tr_b16 v[82:83], v153 offset:0x2200
	ds_read_b64_tr_b16 v[84:85], v153 offset:0x2a00
	ds_read_b64_tr_b16 v[86:87], v153 offset:0x3200
	ds_read_b64_tr_b16 v[88:89], v153 offset:0x3a00
	s_waitcnt lgkmcnt(4)
	s_nop 0
	v_mfma_f32_32x32x16_bf16 v[2:17], v[70:73], v[66:69], v[2:17]
	v_add_f32_e32 v246, v155, v157
	v_add_f32_e32 v247, v214, v215
	v_add_f32_e32 v246, v246, v159
	v_add_f32_e32 v247, v247, v216
	v_mfma_f32_32x32x16_bf16 v[2:17], v[78:81], v[74:77], v[2:17]
	v_add_f32_e32 v246, v246, v193
	v_add_f32_e32 v247, v247, v217
	v_add_f32_e32 v246, v246, v202
	v_add_f32_e32 v247, v247, v194
	ds_read_b64_tr_b16 v[66:67], v153 offset:0x2400
	ds_read_b64_tr_b16 v[68:69], v153 offset:0x2c00
	ds_read_b64_tr_b16 v[74:75], v153 offset:0x3400
	ds_read_b64_tr_b16 v[76:77], v153 offset:0x3c00
	s_waitcnt lgkmcnt(4)
	v_mfma_f32_32x32x16_bf16 v[18:33], v[70:73], v[82:85], v[18:33]
	v_add_f32_e32 v246, v246, v203
	v_add_f32_e32 v247, v247, v195
	v_add_f32_e32 v246, v246, v204
	v_add_f32_e32 v247, v247, v196
	v_mfma_f32_32x32x16_bf16 v[18:33], v[78:81], v[86:89], v[18:33]
	v_add_f32_e32 v246, v246, v205
	v_add_f32_e32 v247, v247, v197
	v_add_f32_e32 v246, v246, v206
	v_add_f32_e32 v247, v247, v198
	ds_read_b64_tr_b16 v[82:83], v153 offset:0x2600
	ds_read_b64_tr_b16 v[84:85], v153 offset:0x2e00
	ds_read_b64_tr_b16 v[86:87], v153 offset:0x3600
	ds_read_b64_tr_b16 v[88:89], v153 offset:0x3e00
	s_waitcnt lgkmcnt(4)
	v_mfma_f32_32x32x16_bf16 v[34:49], v[70:73], v[66:69], v[34:49]
	v_add_f32_e32 v246, v246, v207
	v_add_f32_e32 v247, v247, v199
	v_add_f32_e32 v246, v246, v208
	v_add_f32_e32 v247, v247, v200
	v_mfma_f32_32x32x16_bf16 v[34:49], v[78:81], v[74:77], v[34:49]
	v_add_f32_e32 v246, v246, v209
	v_add_f32_e32 v247, v247, v201
	v_add_f32_e32 v246, v246, v210
	v_add_f32_e32 v247, v247, v249
	s_waitcnt lgkmcnt(0)
	v_mfma_f32_32x32x16_bf16 v[50:65], v[70:73], v[82:85], v[50:65]
	v_add_f32_e32 v246, v246, v211
	v_add_f32_e32 v247, v247, v250
	v_add_f32_e32 v246, v246, v212
	v_add_f32_e32 v247, v247, v251
	v_add_f32_e32 v246, v246, v213
	v_add_f32_e32 v247, v247, v248
	v_add_f32_e32 v246, v246, v247
	v_mov_b32_e32 v247, v246
	s_nop 1
	v_permlane32_swap_b32_e32 v246, v247
	v_add_f32_e32 v246, v246, v247
	v_add_f32_e32 v151, v151, v246
	s_waitcnt vmcnt(0)
	s_xor_b32 s99, s99, 0x6000
	s_xor_b32 s98, s98, 0x4000
	s_cmp_eq_u32 s0, s1
	s_mov_b32 s4, s1
	s_waitcnt vmcnt(0)
	s_barrier
	v_mfma_f32_32x32x16_bf16 v[50:65], v[78:81], v[86:89], v[50:65]
	s_cbranch_scc0 .LBB0_892
	s_lshl_b32 s1, s68, 2
	s_add_i32 s4, s1, 0
	s_and_b32 s0, s0, 1
	s_add_i32 s4, s4, 0x1e000
	s_mul_i32 s1, s0, 0x6000
	v_add_u32_e32 v70, s1, v179
	v_add_u32_e32 v71, v70, v178
	ds_read_b128 v[66:69], v71 offset:32768
	v_add_u32_e32 v153, v70, v180
	v_add_u32_e32 v155, v70, v181
	v_add_u32_e32 v157, v70, v182
	v_add_u32_e32 v159, v70, v183
	v_add_u32_e32 v160, v70, v184
	v_add_u32_e32 v161, v70, v185
	v_add_u32_e32 v162, v70, v186
	v_add_u32_e32 v163, v70, v187
	s_waitcnt lgkmcnt(0)
	v_mfma_f32_32x32x16_bf16 v[82:97], v[66:69], v[142:145], 0
	ds_read_b128 v[66:69], v153 offset:32768
	v_add_u32_e32 v170, v70, v188
	v_add_u32_e32 v171, v70, v189
	v_add_u32_e32 v172, v70, v190
	s_waitcnt lgkmcnt(0)
	v_mfma_f32_32x32x16_bf16 v[82:97], v[66:69], v[138:141], v[82:97]
	ds_read_b128 v[66:69], v155 offset:32768
	s_waitcnt lgkmcnt(0)
	v_mfma_f32_32x32x16_bf16 v[82:97], v[66:69], v[134:137], v[82:97]
	ds_read_b128 v[66:69], v157 offset:32768
	s_waitcnt lgkmcnt(0)
	v_mfma_f32_32x32x16_bf16 v[82:97], v[66:69], v[130:133], v[82:97]
	ds_read_b128 v[66:69], v159 offset:32768
	s_waitcnt lgkmcnt(0)
	v_mfma_f32_32x32x16_bf16 v[82:97], v[66:69], v[126:129], v[82:97]
	ds_read_b128 v[66:69], v160 offset:32768
	s_waitcnt lgkmcnt(0)
	v_mfma_f32_32x32x16_bf16 v[82:97], v[66:69], v[122:125], v[82:97]
	ds_read_b128 v[66:69], v161 offset:32768
	s_waitcnt lgkmcnt(0)
	v_mfma_f32_32x32x16_bf16 v[82:97], v[66:69], v[118:121], v[82:97]
	ds_read_b128 v[66:69], v162 offset:32768
	s_waitcnt lgkmcnt(0)
	v_mfma_f32_32x32x16_bf16 v[82:97], v[66:69], v[114:117], v[82:97]
	ds_read_b128 v[66:69], v163 offset:32768
	s_waitcnt lgkmcnt(0)
	v_mfma_f32_32x32x16_bf16 v[82:97], v[66:69], v[110:113], v[82:97]
	ds_read_b128 v[66:69], v170 offset:32768
	s_waitcnt lgkmcnt(0)
	v_mfma_f32_32x32x16_bf16 v[82:97], v[66:69], v[106:109], v[82:97]
	ds_read_b128 v[66:69], v171 offset:32768
	s_waitcnt lgkmcnt(0)
	v_mfma_f32_32x32x16_bf16 v[82:97], v[66:69], v[102:105], v[82:97]
	ds_read_b128 v[66:69], v172 offset:32768
	s_waitcnt lgkmcnt(0)
	v_mfma_f32_32x32x16_bf16 v[82:97], v[66:69], v[98:101], v[82:97]
	ds_read_b128 v[66:69], v71 offset:45056
	s_waitcnt lgkmcnt(0)
	v_mfma_f32_32x32x16_bf16 v[66:81], v[66:69], v[142:145], 0
	ds_read_b128 v[142:145], v153 offset:45056
	s_waitcnt lgkmcnt(0)
	v_mfma_f32_32x32x16_bf16 v[66:81], v[142:145], v[138:141], v[66:81]
	ds_read_b128 v[138:141], v155 offset:45056
	s_waitcnt lgkmcnt(0)
	v_mfma_f32_32x32x16_bf16 v[66:81], v[138:141], v[134:137], v[66:81]
	ds_read_b128 v[134:137], v157 offset:45056
	s_waitcnt lgkmcnt(0)
	v_mfma_f32_32x32x16_bf16 v[66:81], v[134:137], v[130:133], v[66:81]
	ds_read_b128 v[130:133], v159 offset:45056
	s_waitcnt lgkmcnt(0)
	v_mfma_f32_32x32x16_bf16 v[66:81], v[130:133], v[126:129], v[66:81]
	ds_read_b128 v[126:129], v160 offset:45056
	s_waitcnt lgkmcnt(0)
	v_mfma_f32_32x32x16_bf16 v[66:81], v[126:129], v[122:125], v[66:81]
	ds_read_b128 v[122:125], v161 offset:45056
	s_waitcnt lgkmcnt(0)
	v_mfma_f32_32x32x16_bf16 v[66:81], v[122:125], v[118:121], v[66:81]
	ds_read_b128 v[118:121], v162 offset:45056
	v_exp_f32_e32 v122, v97
	s_waitcnt lgkmcnt(0)
	v_mfma_f32_32x32x16_bf16 v[66:81], v[118:121], v[114:117], v[66:81]
	ds_read_b128 v[114:117], v163 offset:45056
	v_exp_f32_e32 v118, v93
	v_exp_f32_e32 v119, v94
	v_exp_f32_e32 v120, v95
	v_exp_f32_e32 v121, v96
	s_waitcnt lgkmcnt(0)
	v_mfma_f32_32x32x16_bf16 v[66:81], v[114:117], v[110:113], v[66:81]
	ds_read_b128 v[110:113], v170 offset:45056
	v_exp_f32_e32 v114, v89
	v_exp_f32_e32 v115, v90
	v_exp_f32_e32 v116, v91
	v_exp_f32_e32 v117, v92
	v_cvt_pk_bf16_f32 v89, v121, v122
	s_waitcnt lgkmcnt(0)
	v_mfma_f32_32x32x16_bf16 v[66:81], v[110:113], v[106:109], v[66:81]
	ds_read_b128 v[106:109], v171 offset:45056
	v_exp_f32_e32 v110, v85
	v_exp_f32_e32 v111, v86
	v_exp_f32_e32 v112, v87
	v_exp_f32_e32 v113, v88
	v_cvt_pk_bf16_f32 v86, v115, v116
	v_cvt_pk_bf16_f32 v87, v117, v118
	s_waitcnt lgkmcnt(0)
	v_mfma_f32_32x32x16_bf16 v[66:81], v[106:109], v[102:105], v[66:81]
	ds_read_b128 v[102:105], v172 offset:45056
	v_exp_f32_e32 v107, v82
	v_exp_f32_e32 v108, v83
	v_exp_f32_e32 v109, v84
	v_cvt_pk_bf16_f32 v84, v111, v112
	v_cvt_pk_bf16_f32 v85, v113, v114
	v_cvt_pk_bf16_f32 v82, v107, v108
	s_waitcnt lgkmcnt(0)
	v_mfma_f32_32x32x16_bf16 v[66:81], v[102:105], v[98:101], v[66:81]
	v_cvt_pk_bf16_f32 v83, v109, v110
	v_cvt_pk_bf16_f32 v88, v119, v120
	v_lshl_add_u32 v106, s0, 14, v176
	v_permlane32_swap_b32_e32 v82, v84
	v_permlane32_swap_b32_e32 v83, v85
	v_permlane32_swap_b32_e32 v86, v88
	v_permlane32_swap_b32_e32 v87, v89
	ds_read_b64_tr_b16 v[90:91], v106 offset:0
	ds_read_b64_tr_b16 v[92:93], v106 offset:0x800
	ds_read_b64_tr_b16 v[94:95], v106 offset:0x1000
	ds_read_b64_tr_b16 v[96:97], v106 offset:0x1800
	ds_read_b64_tr_b16 v[98:99], v106 offset:0x200
	ds_read_b64_tr_b16 v[100:101], v106 offset:0xa00
	ds_read_b64_tr_b16 v[102:103], v106 offset:0x1200
	ds_read_b64_tr_b16 v[104:105], v106 offset:0x1a00
	s_waitcnt lgkmcnt(4)
	s_nop 0
	v_mfma_f32_32x32x16_bf16 v[2:17], v[82:85], v[90:93], v[2:17]
	s_nop 2
	v_exp_f32_e32 v123, v66
	v_exp_f32_e32 v124, v67
	v_exp_f32_e32 v125, v68
	v_exp_f32_e32 v126, v69
	v_mfma_f32_32x32x16_bf16 v[2:17], v[86:89], v[94:97], v[2:17]
	ds_read_b64_tr_b16 v[66:67], v106 offset:0x400
	ds_read_b64_tr_b16 v[68:69], v106 offset:0xc00
	ds_read_b64_tr_b16 v[90:91], v106 offset:0x1400
	ds_read_b64_tr_b16 v[92:93], v106 offset:0x1c00
	s_waitcnt lgkmcnt(4)
	v_mfma_f32_32x32x16_bf16 v[18:33], v[82:85], v[98:101], v[18:33]
	v_exp_f32_e32 v98, v70
	v_exp_f32_e32 v99, v71
	v_exp_f32_e32 v100, v72
	v_exp_f32_e32 v101, v73
	v_mfma_f32_32x32x16_bf16 v[18:33], v[86:89], v[102:105], v[18:33]
	ds_read_b64_tr_b16 v[70:71], v106 offset:0x600
	ds_read_b64_tr_b16 v[72:73], v106 offset:0xe00
	ds_read_b64_tr_b16 v[94:95], v106 offset:0x1600
	ds_read_b64_tr_b16 v[96:97], v106 offset:0x1e00
	s_waitcnt lgkmcnt(4)
	v_mfma_f32_32x32x16_bf16 v[34:49], v[82:85], v[66:69], v[34:49]
	v_exp_f32_e32 v102, v74
	v_exp_f32_e32 v103, v75
	v_exp_f32_e32 v104, v76
	v_exp_f32_e32 v105, v77
	v_mfma_f32_32x32x16_bf16 v[34:49], v[86:89], v[90:93], v[34:49]
	ds_read_b64_tr_b16 v[74:75], v106 offset:0x2000
	ds_read_b64_tr_b16 v[76:77], v106 offset:0x2800
	ds_read_b64_tr_b16 v[90:91], v106 offset:0x3000
	ds_read_b64_tr_b16 v[92:93], v106 offset:0x3800
	s_waitcnt lgkmcnt(4)
	v_add_f32_e32 v66, v107, v108
	v_add_f32_e32 v67, v123, v124
	v_mfma_f32_32x32x16_bf16 v[50:65], v[82:85], v[70:73], v[50:65]
	v_add_f32_e32 v66, v66, v109
	v_add_f32_e32 v67, v67, v125
	v_exp_f32_e32 v127, v78
	v_add_f32_e32 v66, v66, v110
	v_add_f32_e32 v67, v67, v126
	v_exp_f32_e32 v128, v79
	v_add_f32_e32 v66, v66, v111
	v_add_f32_e32 v67, v67, v98
	v_mfma_f32_32x32x16_bf16 v[50:65], v[86:89], v[94:97], v[50:65]
	v_add_f32_e32 v66, v66, v112
	v_add_f32_e32 v67, v67, v99
	v_exp_f32_e32 v129, v80
	v_add_f32_e32 v66, v66, v113
	v_add_f32_e32 v67, v67, v100
	v_exp_f32_e32 v81, v81
	v_add_f32_e32 v66, v66, v114
	v_add_f32_e32 v67, v67, v101
	v_cvt_pk_bf16_f32 v68, v123, v124
	v_add_f32_e32 v66, v66, v115
	v_add_f32_e32 v67, v67, v102
	v_cvt_pk_bf16_f32 v69, v125, v126
	v_add_f32_e32 v66, v66, v116
	v_add_f32_e32 v67, v67, v103
	v_cvt_pk_bf16_f32 v70, v98, v99
	v_add_f32_e32 v66, v66, v117
	v_add_f32_e32 v67, v67, v104
	v_cvt_pk_bf16_f32 v71, v100, v101
	v_add_f32_e32 v66, v66, v118
	v_add_f32_e32 v67, v67, v105
	v_cvt_pk_bf16_f32 v78, v102, v103
	v_add_f32_e32 v66, v66, v119
	v_add_f32_e32 v67, v67, v127
	v_cvt_pk_bf16_f32 v79, v104, v105
	v_add_f32_e32 v66, v66, v120
	v_add_f32_e32 v67, v67, v128
	v_cvt_pk_bf16_f32 v80, v127, v128
	v_add_f32_e32 v66, v66, v121
	v_add_f32_e32 v67, v67, v129
	v_permlane32_swap_b32_e32 v68, v70
	v_add_f32_e32 v66, v66, v122
	v_add_f32_e32 v67, v67, v81
	v_cvt_pk_bf16_f32 v81, v129, v81
	v_add_f32_e32 v66, v66, v67
	v_mov_b32_e32 v67, v66
	s_nop 1
	v_permlane32_swap_b32_e32 v66, v67
	v_permlane32_swap_b32_e32 v69, v71
	v_permlane32_swap_b32_e32 v78, v80
	v_permlane32_swap_b32_e32 v79, v81
	ds_read_b64_tr_b16 v[82:83], v106 offset:0x2200
	ds_read_b64_tr_b16 v[84:85], v106 offset:0x2a00
	ds_read_b64_tr_b16 v[86:87], v106 offset:0x3200
	ds_read_b64_tr_b16 v[88:89], v106 offset:0x3a00
	s_waitcnt lgkmcnt(4)
	v_mfma_f32_32x32x16_bf16 v[2:17], v[68:71], v[74:77], v[2:17]
	s_nop 0
	v_mfma_f32_32x32x16_bf16 v[2:17], v[78:81], v[90:93], v[2:17]
	ds_read_b64_tr_b16 v[72:73], v106 offset:0x2400
	ds_read_b64_tr_b16 v[74:75], v106 offset:0x2c00
	ds_read_b64_tr_b16 v[90:91], v106 offset:0x3400
	ds_read_b64_tr_b16 v[92:93], v106 offset:0x3c00
	s_waitcnt lgkmcnt(4)
	v_mfma_f32_32x32x16_bf16 v[18:33], v[68:71], v[82:85], v[18:33]
	v_mfma_f32_32x32x16_bf16 v[18:33], v[78:81], v[86:89], v[18:33]
	ds_read_b64_tr_b16 v[82:83], v106 offset:0x2600
	ds_read_b64_tr_b16 v[84:85], v106 offset:0x2e00
	ds_read_b64_tr_b16 v[86:87], v106 offset:0x3600
	ds_read_b64_tr_b16 v[88:89], v106 offset:0x3e00
	s_waitcnt lgkmcnt(4)
	v_mfma_f32_32x32x16_bf16 v[34:49], v[68:71], v[72:75], v[34:49]
	v_mfma_f32_32x32x16_bf16 v[34:49], v[78:81], v[90:93], v[34:49]
	s_waitcnt lgkmcnt(0)
	v_mfma_f32_32x32x16_bf16 v[50:65], v[68:71], v[82:85], v[50:65]
	s_waitcnt vmcnt(0)
	s_barrier
	v_mfma_f32_32x32x16_bf16 v[50:65], v[78:81], v[86:89], v[50:65]
	s_and_saveexec_b64 s[0:1], s[2:3]
	s_cbranch_execz .LBB0_886
	v_add_f32_e32 v66, v66, v67
	v_lshl_add_u32 v68, v1, 2, s4
	v_add_f32_e32 v66, v151, v66
	ds_write_b32 v68, v66
	s_branch .LBB0_886

.LBB0_2312:
	s_xor_b32 s42, s99, 0x6000
	s_add_i32 s42, s53, s42
	s_add_i32 m0, s42, 0x8000
	v_lshl_add_u64 v[66:67], v[160:161], 1, s[40:41]
	global_load_lds_dwordx4 v[66:67], off
	s_add_i32 m0, s42, 0xa000
	v_lshl_add_u64 v[66:67], v[162:163], 1, s[40:41]
	global_load_lds_dwordx4 v[66:67], off
	s_add_i32 m0, s42, 0xc000
	v_lshl_add_u64 v[66:67], v[168:169], 1, s[40:41]
	global_load_lds_dwordx4 v[66:67], off
	s_xor_b32 s42, s98, 0x4000
	s_add_i32 s42, s53, s42
	s_mov_b32 m0, s42
	v_lshl_add_u64 v[66:67], v[170:171], 1, s[14:15]
	global_load_lds_dwordx4 v[66:67], off
	s_add_i32 m0, s42, 0x2000
	v_lshl_add_u64 v[66:67], v[172:173], 1, s[14:15]
	global_load_lds_dwordx4 v[66:67], off
	s_add_u32 s40, s40, 0x30000
	s_addc_u32 s41, s41, 0
	s_add_u32 s14, s14, 0x40000
	s_addc_u32 s15, s15, 0
	s_cmpk_eq_i32 s0, 0xc0
	s_cbranch_scc1 .Lmla1_sw
	.Lmla1_swr:
	v_add_u32_e32 v74, s99, v182
	v_add_u32_e32 v75, v74, v181
	ds_read_b128 v[66:69], v75 offset:32768
	v_add_u32_e32 v76, v74, v183
	ds_read_b128 v[70:73], v76 offset:32768
	v_add_u32_e32 v153, v74, v184
	v_add_u32_e32 v155, v74, v185
	v_add_u32_e32 v157, v74, v186
	v_add_u32_e32 v159, v74, v187
	v_add_u32_e32 v209, v74, v188
	v_add_u32_e32 v218, v74, v189
	s_waitcnt lgkmcnt(0)
	v_mfma_f32_32x32x16_bf16 v[82:97], v[66:69], v[142:145], 0
	ds_read_b128 v[66:69], v153 offset:32768
	v_add_u32_e32 v219, v74, v190
	v_add_u32_e32 v220, v74, v191
	v_add_u32_e32 v221, v74, v192
	v_add_u32_e32 v222, v74, v193
	v_mfma_f32_32x32x16_bf16 v[82:97], v[70:73], v[138:141], v[82:97]
	ds_read_b128 v[70:73], v155 offset:32768
	s_waitcnt lgkmcnt(0)
	v_mfma_f32_32x32x16_bf16 v[82:97], v[66:69], v[134:137], v[82:97]
	ds_read_b128 v[66:69], v157 offset:32768
	v_mfma_f32_32x32x16_bf16 v[82:97], v[70:73], v[130:133], v[82:97]
	ds_read_b128 v[70:73], v159 offset:32768
	s_waitcnt lgkmcnt(0)
	v_mfma_f32_32x32x16_bf16 v[82:97], v[66:69], v[126:129], v[82:97]
	ds_read_b128 v[66:69], v209 offset:32768
	v_mfma_f32_32x32x16_bf16 v[82:97], v[70:73], v[122:125], v[82:97]
	ds_read_b128 v[70:73], v218 offset:32768
	s_waitcnt lgkmcnt(0)
	v_mfma_f32_32x32x16_bf16 v[82:97], v[66:69], v[118:121], v[82:97]
	ds_read_b128 v[66:69], v219 offset:32768
	v_mfma_f32_32x32x16_bf16 v[82:97], v[70:73], v[114:117], v[82:97]
	ds_read_b128 v[70:73], v220 offset:32768
	s_waitcnt lgkmcnt(0)
	v_mfma_f32_32x32x16_bf16 v[82:97], v[66:69], v[110:113], v[82:97]
	ds_read_b128 v[66:69], v221 offset:32768
	v_mfma_f32_32x32x16_bf16 v[82:97], v[70:73], v[106:109], v[82:97]
	ds_read_b128 v[70:73], v222 offset:32768
	s_waitcnt lgkmcnt(0)
	v_mfma_f32_32x32x16_bf16 v[82:97], v[66:69], v[102:105], v[82:97]
	v_mfma_f32_32x32x16_bf16 v[82:97], v[70:73], v[98:101], v[82:97]
	ds_read_b128 v[66:69], v75 offset:45056
	ds_read_b128 v[210:213], v76 offset:45056
	s_nop 9
	v_exp_f32_e32 v226, v86
	v_exp_f32_e32 v227, v87
	v_exp_f32_e32 v228, v88
	s_waitcnt lgkmcnt(0)
	v_mfma_f32_32x32x16_bf16 v[66:81], v[66:69], v[142:145], 0
	v_exp_f32_e32 v229, v89
	v_exp_f32_e32 v230, v90
	v_exp_f32_e32 v231, v91
	v_exp_f32_e32 v232, v92
	v_exp_f32_e32 v233, v93
	v_exp_f32_e32 v234, v94
	v_exp_f32_e32 v235, v95
	v_mfma_f32_32x32x16_bf16 v[66:81], v[210:213], v[138:141], v[66:81]
	ds_read_b128 v[210:213], v153 offset:45056
	ds_read_b128 v[214:217], v155 offset:45056
	v_exp_f32_e32 v155, v82
	v_exp_f32_e32 v236, v96
	v_exp_f32_e32 v237, v97
	v_cvt_pk_bf16_f32 v86, v230, v231
	v_cvt_pk_bf16_f32 v87, v232, v233
	v_cvt_pk_bf16_f32 v88, v234, v235
	s_waitcnt lgkmcnt(0)
	v_mfma_f32_32x32x16_bf16 v[66:81], v[210:213], v[134:137], v[66:81]
	v_cvt_pk_bf16_f32 v89, v236, v237
	v_add_u32_e32 v153, s98, v179
	v_permlane32_swap_b32_e32 v86, v88
	v_permlane32_swap_b32_e32 v87, v89
	v_mfma_f32_32x32x16_bf16 v[66:81], v[214:217], v[130:133], v[66:81]
	ds_read_b128 v[210:213], v157 offset:45056
	ds_read_b128 v[214:217], v159 offset:45056
	v_exp_f32_e32 v157, v83
	v_exp_f32_e32 v159, v84
	v_cvt_pk_bf16_f32 v84, v226, v227
	v_cvt_pk_bf16_f32 v82, v155, v157
	s_nop 1
	v_permlane32_swap_b32_e32 v82, v84
	s_waitcnt lgkmcnt(0)
	v_mfma_f32_32x32x16_bf16 v[66:81], v[210:213], v[126:129], v[66:81]
	v_mfma_f32_32x32x16_bf16 v[66:81], v[214:217], v[122:125], v[66:81]
	ds_read_b128 v[210:213], v209 offset:45056
	ds_read_b128 v[214:217], v218 offset:45056
	v_exp_f32_e32 v209, v85
	v_cvt_pk_bf16_f32 v85, v228, v229
	v_cvt_pk_bf16_f32 v83, v159, v209
	s_nop 1
	v_permlane32_swap_b32_e32 v83, v85
	s_waitcnt lgkmcnt(0)
	v_mfma_f32_32x32x16_bf16 v[66:81], v[210:213], v[118:121], v[66:81]
	ds_read_b128 v[210:213], v219 offset:45056
	v_mfma_f32_32x32x16_bf16 v[66:81], v[214:217], v[114:117], v[66:81]
	ds_read_b128 v[214:217], v220 offset:45056
	ds_read_b128 v[218:221], v221 offset:45056
	ds_read_b128 v[222:225], v222 offset:45056
	s_waitcnt lgkmcnt(0)
	v_mfma_f32_32x32x16_bf16 v[66:81], v[210:213], v[110:113], v[66:81]
	v_mfma_f32_32x32x16_bf16 v[66:81], v[214:217], v[106:109], v[66:81]
	v_mfma_f32_32x32x16_bf16 v[66:81], v[218:221], v[102:105], v[66:81]
	v_mfma_f32_32x32x16_bf16 v[66:81], v[222:225], v[98:101], v[66:81]
	ds_read_b64_tr_b16 v[90:91], v153 offset:0
	ds_read_b64_tr_b16 v[92:93], v153 offset:0x800
	ds_read_b64_tr_b16 v[94:95], v153 offset:0x1000
	ds_read_b64_tr_b16 v[96:97], v153 offset:0x1800
	ds_read_b64_tr_b16 v[210:211], v153 offset:0x200
	ds_read_b64_tr_b16 v[212:213], v153 offset:0xa00
	ds_read_b64_tr_b16 v[214:215], v153 offset:0x1200
	ds_read_b64_tr_b16 v[216:217], v153 offset:0x1a00
	s_waitcnt lgkmcnt(4)
	s_nop 0
	v_mfma_f32_32x32x16_bf16 v[2:17], v[82:85], v[90:93], v[2:17]
	s_nop 9
	v_exp_f32_e32 v218, v66
	v_exp_f32_e32 v219, v67
	v_exp_f32_e32 v220, v68
	v_exp_f32_e32 v221, v69
	v_mfma_f32_32x32x16_bf16 v[2:17], v[86:89], v[94:97], v[2:17]
	ds_read_b64_tr_b16 v[66:67], v153 offset:0x400
	ds_read_b64_tr_b16 v[68:69], v153 offset:0xc00
	ds_read_b64_tr_b16 v[90:91], v153 offset:0x1400
	ds_read_b64_tr_b16 v[92:93], v153 offset:0x1c00
	s_waitcnt lgkmcnt(4)
	v_mfma_f32_32x32x16_bf16 v[18:33], v[82:85], v[210:213], v[18:33]
	v_exp_f32_e32 v210, v70
	v_exp_f32_e32 v211, v71
	v_exp_f32_e32 v212, v72
	v_exp_f32_e32 v213, v73
	v_mfma_f32_32x32x16_bf16 v[18:33], v[86:89], v[214:217], v[18:33]
	ds_read_b64_tr_b16 v[70:71], v153 offset:0x600
	ds_read_b64_tr_b16 v[72:73], v153 offset:0xe00
	ds_read_b64_tr_b16 v[94:95], v153 offset:0x1600
	ds_read_b64_tr_b16 v[96:97], v153 offset:0x1e00
	s_waitcnt lgkmcnt(4)
	v_mfma_f32_32x32x16_bf16 v[34:49], v[82:85], v[66:69], v[34:49]
	v_exp_f32_e32 v214, v74
	v_exp_f32_e32 v215, v75
	v_exp_f32_e32 v216, v76
	v_exp_f32_e32 v217, v77
	v_mfma_f32_32x32x16_bf16 v[34:49], v[86:89], v[90:93], v[34:49]
	ds_read_b64_tr_b16 v[66:67], v153 offset:0x2000
	ds_read_b64_tr_b16 v[68:69], v153 offset:0x2800
	ds_read_b64_tr_b16 v[74:75], v153 offset:0x3000
	ds_read_b64_tr_b16 v[76:77], v153 offset:0x3800
	s_waitcnt lgkmcnt(4)
	v_exp_f32_e32 v90, v78
	v_mfma_f32_32x32x16_bf16 v[50:65], v[82:85], v[70:73], v[50:65]
	v_exp_f32_e32 v91, v79
	v_cvt_pk_bf16_f32 v72, v210, v211
	v_cvt_pk_bf16_f32 v73, v212, v213
	v_mfma_f32_32x32x16_bf16 v[50:65], v[86:89], v[94:97], v[50:65]
	v_exp_f32_e32 v92, v80
	v_exp_f32_e32 v248, v81
	v_cvt_pk_bf16_f32 v78, v214, v215
	v_cvt_pk_bf16_f32 v79, v216, v217
	v_cvt_pk_bf16_f32 v80, v90, v91
	v_cvt_pk_bf16_f32 v70, v218, v219
	v_cvt_pk_bf16_f32 v71, v220, v221
	v_permlane32_swap_b32_e32 v78, v80
	v_cvt_pk_bf16_f32 v81, v92, v248
	v_permlane32_swap_b32_e32 v70, v72
	v_permlane32_swap_b32_e32 v71, v73
	s_nop 0
	v_permlane32_swap_b32_e32 v79, v81
	ds_read_b64_tr_b16 v[82:83], v153 offset:0x2200
	ds_read_b64_tr_b16 v[84:85], v153 offset:0x2a00
	ds_read_b64_tr_b16 v[86:87], v153 offset:0x3200
	ds_read_b64_tr_b16 v[88:89], v153 offset:0x3a00
	s_waitcnt lgkmcnt(4)
	s_nop 0
	v_mfma_f32_32x32x16_bf16 v[2:17], v[70:73], v[66:69], v[2:17]
	v_add_f32_e32 v246, v155, v157
	v_add_f32_e32 v247, v218, v219
	v_add_f32_e32 v246, v246, v159
	v_add_f32_e32 v247, v247, v220
	v_mfma_f32_32x32x16_bf16 v[2:17], v[78:81], v[74:77], v[2:17]
	v_add_f32_e32 v246, v246, v209
	v_add_f32_e32 v247, v247, v221
	v_add_f32_e32 v246, v246, v226
	v_add_f32_e32 v247, v247, v210
	ds_read_b64_tr_b16 v[66:67], v153 offset:0x2400
	ds_read_b64_tr_b16 v[68:69], v153 offset:0x2c00
	ds_read_b64_tr_b16 v[74:75], v153 offset:0x3400
	ds_read_b64_tr_b16 v[76:77], v153 offset:0x3c00
	s_waitcnt lgkmcnt(4)
	v_mfma_f32_32x32x16_bf16 v[18:33], v[70:73], v[82:85], v[18:33]
	v_add_f32_e32 v246, v246, v227
	v_add_f32_e32 v247, v247, v211
	v_add_f32_e32 v246, v246, v228
	v_add_f32_e32 v247, v247, v212
	v_mfma_f32_32x32x16_bf16 v[18:33], v[78:81], v[86:89], v[18:33]
	v_add_f32_e32 v246, v246, v229
	v_add_f32_e32 v247, v247, v213
	v_add_f32_e32 v246, v246, v230
	v_add_f32_e32 v247, v247, v214
	ds_read_b64_tr_b16 v[82:83], v153 offset:0x2600
	ds_read_b64_tr_b16 v[84:85], v153 offset:0x2e00
	ds_read_b64_tr_b16 v[86:87], v153 offset:0x3600
	ds_read_b64_tr_b16 v[88:89], v153 offset:0x3e00
	s_waitcnt lgkmcnt(4)
	v_mfma_f32_32x32x16_bf16 v[34:49], v[70:73], v[66:69], v[34:49]
	v_add_f32_e32 v246, v246, v231
	v_add_f32_e32 v247, v247, v215
	v_add_f32_e32 v246, v246, v232
	v_add_f32_e32 v247, v247, v216
	v_mfma_f32_32x32x16_bf16 v[34:49], v[78:81], v[74:77], v[34:49]
	v_add_f32_e32 v246, v246, v233
	v_add_f32_e32 v247, v247, v217
	v_add_f32_e32 v246, v246, v234
	v_add_f32_e32 v247, v247, v90
	s_waitcnt lgkmcnt(0)
	v_mfma_f32_32x32x16_bf16 v[50:65], v[70:73], v[82:85], v[50:65]
	v_add_f32_e32 v246, v246, v235
	v_add_f32_e32 v247, v247, v91
	v_add_f32_e32 v246, v246, v236
	v_add_f32_e32 v247, v247, v92
	v_add_f32_e32 v246, v246, v237
	v_add_f32_e32 v247, v247, v248
	v_add_f32_e32 v246, v246, v247
	v_mov_b32_e32 v247, v246
	s_nop 1
	v_permlane32_swap_b32_e32 v246, v247
	v_add_f32_e32 v246, v246, v247
	v_add_f32_e32 v151, v151, v246
	s_waitcnt vmcnt(0)
	s_add_u32 s0, s0, 64
	s_xor_b32 s99, s99, 0x6000
	s_xor_b32 s98, s98, 0x4000
	s_cmpk_eq_i32 s0, 0x4100
	s_waitcnt vmcnt(0)
	s_barrier
	v_mfma_f32_32x32x16_bf16 v[50:65], v[78:81], v[86:89], v[50:65]
	s_cbranch_scc0 .LBB0_2312
	s_lshl_b32 s0, s52, 2
	s_add_i32 s4, s0, 0
	s_add_i32 s4, s4, 0x1e000
	ds_read_b128 v[66:69], v196
	ds_read_b128 v[70:73], v197
	s_waitcnt lgkmcnt(1)
	v_mfma_f32_32x32x16_bf16 v[82:97], v[66:69], v[142:145], 0
	s_waitcnt lgkmcnt(0)
	v_mfma_f32_32x32x16_bf16 v[82:97], v[70:73], v[138:141], v[82:97]
	ds_read_b128 v[66:69], v198
	ds_read_b128 v[70:73], v199
	s_waitcnt lgkmcnt(1)
	v_mfma_f32_32x32x16_bf16 v[82:97], v[66:69], v[134:137], v[82:97]
	s_waitcnt lgkmcnt(0)
	v_mfma_f32_32x32x16_bf16 v[82:97], v[70:73], v[130:133], v[82:97]
	ds_read_b128 v[66:69], v200
	ds_read_b128 v[70:73], v201
	s_waitcnt lgkmcnt(1)
	v_mfma_f32_32x32x16_bf16 v[82:97], v[66:69], v[126:129], v[82:97]
	s_waitcnt lgkmcnt(0)
	v_mfma_f32_32x32x16_bf16 v[82:97], v[70:73], v[122:125], v[82:97]
	ds_read_b128 v[66:69], v202
	ds_read_b128 v[70:73], v203
	s_waitcnt lgkmcnt(1)
	v_mfma_f32_32x32x16_bf16 v[82:97], v[66:69], v[118:121], v[82:97]
	s_waitcnt lgkmcnt(0)
	v_mfma_f32_32x32x16_bf16 v[82:97], v[70:73], v[114:117], v[82:97]
	ds_read_b128 v[66:69], v204
	ds_read_b128 v[70:73], v205
	s_waitcnt lgkmcnt(1)
	v_mfma_f32_32x32x16_bf16 v[82:97], v[66:69], v[110:113], v[82:97]
	s_waitcnt lgkmcnt(0)
	v_mfma_f32_32x32x16_bf16 v[82:97], v[70:73], v[106:109], v[82:97]
	ds_read_b128 v[66:69], v206
	ds_read_b128 v[70:73], v207
	s_waitcnt lgkmcnt(1)
	v_mfma_f32_32x32x16_bf16 v[82:97], v[66:69], v[102:105], v[82:97]
	s_waitcnt lgkmcnt(0)
	v_mfma_f32_32x32x16_bf16 v[82:97], v[70:73], v[98:101], v[82:97]
	ds_read_b128 v[66:69], v196 offset:12288
	ds_read_b128 v[160:163], v197 offset:12288
	s_waitcnt lgkmcnt(1)
	v_mfma_f32_32x32x16_bf16 v[66:81], v[66:69], v[142:145], 0
	s_waitcnt lgkmcnt(0)
	v_mfma_f32_32x32x16_bf16 v[66:81], v[160:163], v[138:141], v[66:81]
	ds_read_b128 v[138:141], v198 offset:12288
	ds_read_b128 v[142:145], v199 offset:12288
	s_waitcnt lgkmcnt(1)
	v_mfma_f32_32x32x16_bf16 v[66:81], v[138:141], v[134:137], v[66:81]
	s_waitcnt lgkmcnt(0)
	v_mfma_f32_32x32x16_bf16 v[66:81], v[142:145], v[130:133], v[66:81]
	ds_read_b128 v[130:133], v200 offset:12288
	ds_read_b128 v[134:137], v201 offset:12288
	s_waitcnt lgkmcnt(1)
	v_mfma_f32_32x32x16_bf16 v[66:81], v[130:133], v[126:129], v[66:81]
	v_exp_f32_e32 v130, v82
	v_exp_f32_e32 v131, v83
	v_exp_f32_e32 v132, v84
	v_cvt_pk_bf16_f32 v82, v130, v131
	s_waitcnt lgkmcnt(0)
	v_mfma_f32_32x32x16_bf16 v[66:81], v[134:137], v[122:125], v[66:81]
	ds_read_b128 v[122:125], v202 offset:12288
	ds_read_b128 v[126:129], v203 offset:12288
	s_waitcnt lgkmcnt(1)
	v_mfma_f32_32x32x16_bf16 v[66:81], v[122:125], v[118:121], v[66:81]
	s_waitcnt lgkmcnt(0)
	v_mfma_f32_32x32x16_bf16 v[66:81], v[126:129], v[114:117], v[66:81]
	ds_read_b128 v[114:117], v204 offset:12288
	ds_read_b128 v[118:121], v205 offset:12288
	ds_read_b128 v[122:125], v206 offset:12288
	ds_read_b128 v[126:129], v207 offset:12288
	s_waitcnt lgkmcnt(3)
	v_mfma_f32_32x32x16_bf16 v[66:81], v[114:117], v[110:113], v[66:81]
	v_exp_f32_e32 v110, v85
	v_exp_f32_e32 v111, v86
	v_exp_f32_e32 v112, v87
	v_exp_f32_e32 v113, v88
	v_exp_f32_e32 v114, v89
	v_exp_f32_e32 v115, v90
	v_exp_f32_e32 v116, v91
	s_waitcnt lgkmcnt(2)
	v_mfma_f32_32x32x16_bf16 v[66:81], v[118:121], v[106:109], v[66:81]
	v_exp_f32_e32 v106, v92
	v_exp_f32_e32 v107, v93
	v_exp_f32_e32 v108, v94
	v_exp_f32_e32 v109, v95
	v_exp_f32_e32 v117, v96
	v_exp_f32_e32 v118, v97
	v_cvt_pk_bf16_f32 v83, v132, v110
	s_waitcnt lgkmcnt(1)
	v_mfma_f32_32x32x16_bf16 v[66:81], v[122:125], v[102:105], v[66:81]
	v_cvt_pk_bf16_f32 v84, v111, v112
	v_cvt_pk_bf16_f32 v85, v113, v114
	v_cvt_pk_bf16_f32 v86, v115, v116
	v_cvt_pk_bf16_f32 v87, v106, v107
	v_cvt_pk_bf16_f32 v88, v108, v109
	v_cvt_pk_bf16_f32 v89, v117, v118
	v_permlane32_swap_b32_e32 v82, v84
	s_waitcnt lgkmcnt(0)
	v_mfma_f32_32x32x16_bf16 v[66:81], v[126:129], v[98:101], v[66:81]
	v_permlane32_swap_b32_e32 v83, v85
	v_permlane32_swap_b32_e32 v86, v88
	v_permlane32_swap_b32_e32 v87, v89
	ds_read_b64_tr_b16 v[90:91], v208 offset:0
	ds_read_b64_tr_b16 v[92:93], v208 offset:0x800
	ds_read_b64_tr_b16 v[94:95], v208 offset:0x1000
	ds_read_b64_tr_b16 v[96:97], v208 offset:0x1800
	ds_read_b64_tr_b16 v[98:99], v208 offset:0x200
	ds_read_b64_tr_b16 v[100:101], v208 offset:0xa00
	ds_read_b64_tr_b16 v[102:103], v208 offset:0x1200
	ds_read_b64_tr_b16 v[104:105], v208 offset:0x1a00
	s_waitcnt lgkmcnt(4)
	s_nop 0
	v_mfma_f32_32x32x16_bf16 v[2:17], v[82:85], v[90:93], v[2:17]
	s_nop 6
	v_exp_f32_e32 v119, v66
	v_exp_f32_e32 v120, v67
	v_exp_f32_e32 v121, v68
	v_exp_f32_e32 v122, v69
	v_mfma_f32_32x32x16_bf16 v[2:17], v[86:89], v[94:97], v[2:17]
	ds_read_b64_tr_b16 v[66:67], v208 offset:0x400
	ds_read_b64_tr_b16 v[68:69], v208 offset:0xc00
	ds_read_b64_tr_b16 v[90:91], v208 offset:0x1400
	ds_read_b64_tr_b16 v[92:93], v208 offset:0x1c00
	s_waitcnt lgkmcnt(4)
	v_mfma_f32_32x32x16_bf16 v[18:33], v[82:85], v[98:101], v[18:33]
	v_exp_f32_e32 v98, v70
	v_exp_f32_e32 v99, v71
	v_exp_f32_e32 v100, v72
	v_exp_f32_e32 v101, v73
	v_mfma_f32_32x32x16_bf16 v[18:33], v[86:89], v[102:105], v[18:33]
	ds_read_b64_tr_b16 v[70:71], v208 offset:0x600
	ds_read_b64_tr_b16 v[72:73], v208 offset:0xe00
	ds_read_b64_tr_b16 v[94:95], v208 offset:0x1600
	ds_read_b64_tr_b16 v[96:97], v208 offset:0x1e00
	s_waitcnt lgkmcnt(4)
	v_mfma_f32_32x32x16_bf16 v[34:49], v[82:85], v[66:69], v[34:49]
	v_exp_f32_e32 v102, v74
	v_exp_f32_e32 v103, v75
	v_exp_f32_e32 v104, v76
	v_exp_f32_e32 v105, v77
	v_mfma_f32_32x32x16_bf16 v[34:49], v[86:89], v[90:93], v[34:49]
	ds_read_b64_tr_b16 v[74:75], v208 offset:0x2000
	ds_read_b64_tr_b16 v[76:77], v208 offset:0x2800
	ds_read_b64_tr_b16 v[90:91], v208 offset:0x3000
	ds_read_b64_tr_b16 v[92:93], v208 offset:0x3800
	s_waitcnt lgkmcnt(4)
	v_add_f32_e32 v66, v130, v131
	v_add_f32_e32 v67, v119, v120
	v_mfma_f32_32x32x16_bf16 v[50:65], v[82:85], v[70:73], v[50:65]
	v_add_f32_e32 v66, v66, v132
	v_add_f32_e32 v67, v67, v121
	v_exp_f32_e32 v123, v78
	v_add_f32_e32 v66, v66, v110
	v_add_f32_e32 v67, v67, v122
	v_exp_f32_e32 v124, v79
	v_add_f32_e32 v66, v66, v111
	v_add_f32_e32 v67, v67, v98
	v_mfma_f32_32x32x16_bf16 v[50:65], v[86:89], v[94:97], v[50:65]
	v_add_f32_e32 v66, v66, v112
	v_add_f32_e32 v67, v67, v99
	v_exp_f32_e32 v125, v80
	v_add_f32_e32 v66, v66, v113
	v_add_f32_e32 v67, v67, v100
	v_exp_f32_e32 v81, v81
	v_add_f32_e32 v66, v66, v114
	v_add_f32_e32 v67, v67, v101
	v_cvt_pk_bf16_f32 v68, v119, v120
	v_add_f32_e32 v66, v66, v115
	v_add_f32_e32 v67, v67, v102
	v_cvt_pk_bf16_f32 v69, v121, v122
	v_add_f32_e32 v66, v66, v116
	v_add_f32_e32 v67, v67, v103
	v_cvt_pk_bf16_f32 v70, v98, v99
	v_add_f32_e32 v66, v66, v106
	v_add_f32_e32 v67, v67, v104
	v_cvt_pk_bf16_f32 v71, v100, v101
	v_add_f32_e32 v66, v66, v107
	v_add_f32_e32 v67, v67, v105
	v_cvt_pk_bf16_f32 v78, v102, v103
	v_add_f32_e32 v66, v66, v108
	v_add_f32_e32 v67, v67, v123
	v_cvt_pk_bf16_f32 v79, v104, v105
	v_add_f32_e32 v66, v66, v109
	v_add_f32_e32 v67, v67, v124
	v_cvt_pk_bf16_f32 v80, v123, v124
	v_add_f32_e32 v66, v66, v117
	v_add_f32_e32 v67, v67, v125
	v_permlane32_swap_b32_e32 v68, v70
	v_add_f32_e32 v66, v66, v118
	v_add_f32_e32 v67, v67, v81
	v_cvt_pk_bf16_f32 v81, v125, v81
	v_add_f32_e32 v66, v66, v67
	v_mov_b32_e32 v67, v66
	s_nop 1
	v_permlane32_swap_b32_e32 v66, v67
	v_permlane32_swap_b32_e32 v69, v71
	v_permlane32_swap_b32_e32 v78, v80
	v_permlane32_swap_b32_e32 v79, v81
	ds_read_b64_tr_b16 v[82:83], v208 offset:0x2200
	ds_read_b64_tr_b16 v[84:85], v208 offset:0x2a00
	ds_read_b64_tr_b16 v[86:87], v208 offset:0x3200
	ds_read_b64_tr_b16 v[88:89], v208 offset:0x3a00
	s_waitcnt lgkmcnt(4)
	v_mfma_f32_32x32x16_bf16 v[2:17], v[68:71], v[74:77], v[2:17]
	s_nop 0
	v_mfma_f32_32x32x16_bf16 v[2:17], v[78:81], v[90:93], v[2:17]
	ds_read_b64_tr_b16 v[72:73], v208 offset:0x2400
	ds_read_b64_tr_b16 v[74:75], v208 offset:0x2c00
	ds_read_b64_tr_b16 v[90:91], v208 offset:0x3400
	ds_read_b64_tr_b16 v[92:93], v208 offset:0x3c00
	s_waitcnt lgkmcnt(4)
	v_mfma_f32_32x32x16_bf16 v[18:33], v[68:71], v[82:85], v[18:33]
	v_mfma_f32_32x32x16_bf16 v[18:33], v[78:81], v[86:89], v[18:33]
	ds_read_b64_tr_b16 v[82:83], v208 offset:0x2600
	ds_read_b64_tr_b16 v[84:85], v208 offset:0x2e00
	ds_read_b64_tr_b16 v[86:87], v208 offset:0x3600
	ds_read_b64_tr_b16 v[88:89], v208 offset:0x3e00
	s_waitcnt lgkmcnt(4)
	v_mfma_f32_32x32x16_bf16 v[34:49], v[68:71], v[72:75], v[34:49]
	v_mfma_f32_32x32x16_bf16 v[34:49], v[78:81], v[90:93], v[34:49]
	s_waitcnt lgkmcnt(0)
	v_mfma_f32_32x32x16_bf16 v[50:65], v[68:71], v[82:85], v[50:65]
	s_waitcnt vmcnt(0)
	s_barrier
	v_mfma_f32_32x32x16_bf16 v[50:65], v[78:81], v[86:89], v[50:65]
	s_and_saveexec_b64 s[0:1], s[2:3]
	s_cbranch_execz .LBB0_2310
	v_add_f32_e32 v66, v66, v67
	v_lshl_add_u32 v68, v165, 2, s4
	v_add_f32_e32 v66, v151, v66
	ds_write_b32 v68, v66
	s_branch .LBB0_2310
